# v19: v18 + ret_scan step loop: the 12 next-step K/V loads use one scalar base (walking SGPR pair) + two per-lane offsets instead of ~110 VALU of 64-bit address arithmetic per step
# baseline (speedup 1.0000x reference)
; __device__ __forceinline__ void ret_scan(const bf16* proj, bf16* ST, bf16* FS, const float* dexp, LAS unsigned char* lds, int vb, int nb, int tid_in, int wave) {
;     ...
;                 for (int m = 0; m < 8; ++m)
; #pragma unroll
;                     for (int nt = 0; nt < 2; ++nt) { const int v = (2 * wave + nt) * 16 + qi, d0 = dsl * 128 + m * 16 + 4 * g; *(v2u*)(dst_prev + v * 256 + d0) = stq[m][nt]; }
;             }
;             if (step == nsteps) break;
;             if (step + 1 < nsteps) { const int n1 = dir == 0 ? step + 1 : N - 2 - step, rowb = base + n1 * 128;
; #pragma unroll
;                 for (int i = 0; i < 4; ++i) { const int id = tid + 512 * i, j = id >> 4, ch = id & 15; kr[i] = *(const v4u*)(proj + (size_t)(rowb + j) * NIN + C_RK + h * 256 + dsl * 128 + ch * 8); }
; #pragma unroll
;                 for (int i = 0; i < 8; ++i) { const int id = tid + 512 * i, j = id >> 5, ch = id & 31; vr[i] = *(const v4u*)(proj + (size_t)(rowb + j) * NIN + C_RV + h * 256 + ch * 8); } }
.LBB0_418:
	s_cmp_eq_u32 s59, s52
	v_lshl_add_u64 v[114:115], s[50:51], 0, v[182:183]
	s_cselect_b64 s[42:43], -1, 0
	v_lshl_add_u64 v[116:117], v[160:161], 1, v[114:115]
	v_lshl_add_u64 v[114:115], v[162:163], 1, v[114:115]
	s_add_i32 s64, s59, 1
	s_and_b64 vcc, exec, s[42:43]
	global_store_dwordx2 v[116:117], v[118:119], off
	global_store_dwordx2 v[114:115], v[120:121], off
	global_store_dwordx2 v[116:117], v[122:123], off offset:32
	global_store_dwordx2 v[114:115], v[124:125], off offset:32
	global_store_dwordx2 v[116:117], v[126:127], off offset:64
	global_store_dwordx2 v[114:115], v[128:129], off offset:64
	global_store_dwordx2 v[116:117], v[130:131], off offset:96
	global_store_dwordx2 v[114:115], v[132:133], off offset:96
	global_store_dwordx2 v[116:117], v[134:135], off offset:128
	global_store_dwordx2 v[114:115], v[136:137], off offset:128
	global_store_dwordx2 v[116:117], v[138:139], off offset:160
	global_store_dwordx2 v[114:115], v[140:141], off offset:160
	global_store_dwordx2 v[116:117], v[142:143], off offset:192
	global_store_dwordx2 v[114:115], v[144:145], off offset:192
	global_store_dwordx2 v[116:117], v[168:169], off offset:224
	global_store_dwordx2 v[114:115], v[170:171], off offset:224
	s_cbranch_vccnz .LBB0_415
	s_cmp_ge_u32 s64, s52
	s_cbranch_scc1 .LBB0_414
	s_sub_i32 s37, 14, s59
	s_and_b64 s[30:31], s[4:5], exec
	s_cselect_b32 s30, s64, s37
	s_lshl_b32 s30, s30, 7
	s_add_i32 s50, s30, s53
	s_mov_b32 s37, s63
	v_mov_b32_e32 v165, v183
	v_mov_b32_e32 v167, v183
	v_mad_u32_u24 v236, v1, s33, v164
	v_mad_u32_u24 v237, v174, s33, v166
	s_mul_i32 s100, s50, s33
	s_add_u32 s100, s6, s100
	s_addc_u32 s101, s7, 0
	s_add_u32 s100, s100, s62
	s_addc_u32 s101, s101, 0
	s_add_u32 s30, s100, s36
	s_addc_u32 s31, s101, 0
	s_add_u32 s30, s30, 0x4000
	s_addc_u32 s31, s31, 0
	global_load_dwordx4 v[2:5], v236, s[30:31]
	s_add_u32 s30, s30, 0xe0000
	s_addc_u32 s31, s31, 0
	global_load_dwordx4 v[6:9], v236, s[30:31]
	s_add_u32 s30, s30, 0xe0000
	s_addc_u32 s31, s31, 0
	global_load_dwordx4 v[10:13], v236, s[30:31]
	s_add_u32 s30, s30, 0xe0000
	s_addc_u32 s31, s31, 0
	global_load_dwordx4 v[14:17], v236, s[30:31]
	s_add_u32 s30, s100, 0x5000
	s_addc_u32 s31, s101, 0
	global_load_dwordx4 v[18:21], v237, s[30:31]
	s_add_u32 s30, s30, 0x70000
	s_addc_u32 s31, s31, 0
	global_load_dwordx4 v[22:25], v237, s[30:31]
	s_add_u32 s30, s30, 0x70000
	s_addc_u32 s31, s31, 0
	global_load_dwordx4 v[26:29], v237, s[30:31]
	s_add_u32 s30, s30, 0x70000
	s_addc_u32 s31, s31, 0
	global_load_dwordx4 v[30:33], v237, s[30:31]
	s_add_u32 s30, s30, 0x70000
	s_addc_u32 s31, s31, 0
	global_load_dwordx4 v[34:37], v237, s[30:31]
	s_add_u32 s30, s30, 0x70000
	s_addc_u32 s31, s31, 0
	global_load_dwordx4 v[38:41], v237, s[30:31]
	s_add_u32 s30, s30, 0x70000
	s_addc_u32 s31, s31, 0
	global_load_dwordx4 v[42:45], v237, s[30:31]
	s_add_u32 s30, s30, 0x70000
	s_addc_u32 s31, s31, 0
	global_load_dwordx4 v[46:49], v237, s[30:31]
	s_branch .LBB0_414
